# in-projection epilogue stores lane-transposed too (address delta per lane), all four GEMM epilogues now write 64B-contiguous lane groups
# speedup vs baseline: 1.0026x; 1.0026x over previous
; #define PG8_STAGE(bufoff, gbase, voff) do { _Pragma("unroll") for (int _i = 0; _i < 2; ++_i) \
;         __builtin_amdgcn_global_load_lds((const unsigned*)((const char*)(gbase) + (voff)[_i]), (PG8_LAS unsigned*)(lds + (bufoff) + ldsw + _i * 8192), 16, 0, 0); } while (0)
; #define PG8_STAGEA(bufoff, gbase, voff) do { _Pragma("unroll") for (int _i = 0; _i < 2; ++_i) \
;         __builtin_amdgcn_global_load_lds((const unsigned*)((const char*)(gbase) + (voff)[_i]), (PG8_LAS unsigned*)(lds + (bufoff) + ldsw + _i * 8192), 16, 0, A_AUX); } while (0)
; #define PG8_WAIT_V(n) asm volatile("s_waitcnt vmcnt(" #n ")" ::: "memory")
; #define PG8_BAR __builtin_amdgcn_s_barrier()
;     ...
;     const char* cA = (const char*)g.A + (size_t)cur.pm * tstep; const char* cB = (const char*)g.Bt + (size_t)cur.pn * tstep;
;     S.a_ready(cur);
;     if constexpr (SP2) {
;         PG8_STAGE(PG8_SB(0, 0), cB, voffB); PG8_STAGE(PG8_SB(0, 1), cB + hstep, voffB); PG8_STAGEA(PG8_SA(0, 0), cA, voffA); PG8_STAGEA(PG8_SA(0, 1), cA + hstep, voffA);
;         if (wr == 1) PG8_BAR;
;         PG8_WAIT_V(2); PG8_BAR;
;         PG8_STAGE(PG8_SB(1, 0), cB + kstep, voffB); PG8_STAGEA(PG8_SA(1, 0), cA + kstep, voffA); PG8_STAGE(PG8_SB(1, 1), cB + hstep + kstep, voffB);
;         PG8_WAIT_V(6); PG8_BAR;
;     __device__ __forceinline__ void operator()(const f32x4 (&acc)[2][2][4][2], const Unit& u, int wr, int wc, int fr, int fq) const {
;         const int row0 = u.pm * BM + wr * 64 + fr; const int colt = u.pn * BM; const int col0 = colt + wc * 32 + 8 * fq;
;         const bool rot_wave = (colt < 640) && ((wc & 1) == 0);
.LBB0_180:
	v_readlane_b32 s22, v244, 21
	v_readlane_b32 s44, v246, 27
	v_readlane_b32 s23, v244, 22
	s_mul_i32 s76, s22, 0x500
	v_readlane_b32 s48, v246, 31
	v_readlane_b32 s49, v246, 32
	v_readlane_b32 s50, v246, 33
	v_readlane_b32 s51, v246, 34
	v_readlane_b32 s56, v246, 39
	v_readlane_b32 s57, v246, 40
	s_lshl_b64 s[22:23], s[76:77], 2
	v_readlane_b32 s58, v246, 41
	v_readlane_b32 s59, v246, 42
	s_mov_b64 s[48:49], s[56:57]
	v_readlane_b32 s38, v244, 10
	s_add_u32 s22, s48, s22
	v_mov_b32_e32 v179, v1
	v_readlane_b32 s39, v244, 11
	s_addc_u32 s23, s49, s23
	s_and_b32 s16, s16, 3
	s_add_i32 m0, s61, 0x18000
	v_lshl_add_u64 v[2:3], v[2:3], 0, s[8:9]
	v_lshl_add_u64 v[14:15], s[38:39], 0, v[178:179]
	v_mov_b32_e32 v177, v1
	s_lshl_b32 s36, s1, 13
	s_lshl_b32 s65, s16, 5
	s_lshl_b32 s37, s16, 12
	s_waitcnt vmcnt(2)
	s_barrier
	global_load_lds_dwordx4 v[2:3], off
	v_lshl_add_u64 v[2:3], v[4:5], 0, s[8:9]
	s_add_i32 m0, s61, 0x1a000
	s_add_i32 s72, s61, 0x8000
	s_add_i32 s73, s61, 0xa000
	v_lshl_add_u64 v[16:17], s[38:39], 0, v[176:177]
	global_load_lds_dwordx4 v[2:3], off
	v_lshl_add_u64 v[2:3], v[14:15], 0, s[8:9]
	s_mov_b32 m0, s72
	s_add_u32 s16, s40, 0x40080
	global_load_lds_dwordx4 v[2:3], off
	v_lshl_add_u64 v[2:3], v[16:17], 0, s[8:9]
	s_mov_b32 m0, s73
	s_addc_u32 s17, s41, 0
	global_load_lds_dwordx4 v[2:3], off
	s_add_i32 m0, s61, 0x1c000
	v_lshl_add_u64 v[2:3], s[16:17], 0, v[0:1]
	global_load_lds_dwordx4 v[2:3], off
	v_lshl_add_u64 v[2:3], s[16:17], 0, v[174:175]
	s_add_i32 m0, s61, 0x1e000
	v_bfe_u32 v4, v7, 4, 2
	global_load_lds_dwordx4 v[2:3], off
	v_readlane_b32 s46, v246, 29
	v_readlane_b32 s47, v246, 30
	v_and_b32_e32 v3, 15, v7
	v_lshlrev_b32_e32 v2, 4, v4
	v_lshlrev_b32_e32 v5, 2, v7
	s_cmpk_lt_u32 s0, 0x100
	v_lshl_or_b32 v199, s1, 6, v3
	v_and_b32_e32 v248, 3, v192
	v_bfe_u32 v249, v192, 4, 2
	v_sub_u32_e32 v253, v248, v249
	v_lshlrev_b32_e32 v248, 4, v248
	v_bfe_u32 v249, v192, 2, 4
	v_add_lshl_u32 v248, v248, v249, 2
	v_and_b32_e32 v252, 15, v192
	v_sub_u32_e32 v252, v249, v252
	v_mul_i32_i24_e32 v252, 0xa00, v252
	v_lshl_add_u32 v252, v253, 4, v252
	v_ashrrev_i32_e32 v253, 31, v252
	v_lshl_or_b32 v3, v3, 6, v2
	v_and_b32_e32 v5, 32, v5
	s_cselect_b64 s[46:47], -1, 0
	s_bitcmp0_b32 s0, 6
	v_readlane_b32 s0, v246, 4
	v_bitop3_b32 v7, v3, s36, v5 bitop3:0xde
	v_bitop3_b32 v201, v3, s37, v5 bitop3:0xde
	v_mov_b32_e32 v3, v1
	v_readlane_b32 s1, v246, 5
	s_waitcnt vmcnt(6)
	v_readlane_b32 s45, v246, 28
	v_readlane_b32 s52, v246, 35
	v_lshl_add_u64 v[180:181], s[0:1], 0, v[2:3]
	v_lshlrev_b32_e32 v2, 14, v11
	v_and_b32_e32 v2, 0xffff8000, v2
	v_lshl_add_u32 v2, v10, 11, v2
	v_and_b32_e32 v3, 1, v11
	v_lshl_or_b32 v2, v3, 6, v2
	v_lshl_add_u32 v182, v12, 1, v2
	v_lshlrev_b32_e32 v2, 14, v6
	v_and_b32_e32 v2, 0xffff8000, v2
	v_lshl_add_u32 v2, v8, 11, v2
	v_and_b32_e32 v3, 1, v6
	v_readlane_b32 s0, v244, 6
	v_lshl_or_b32 v2, v3, 6, v2
	v_readlane_b32 s1, v244, 7
	s_mov_b64 s[50:51], s[58:59]
	v_lshlrev_b32_e32 v200, 3, v4
	s_mov_b32 s76, 0
	s_cselect_b64 s[48:49], -1, 0
	v_cmp_gt_u32_e64 s[36:37], 2, v4
	v_lshlrev_b32_e32 v202, 2, v4
	v_mov_b32_e32 v183, v1
	v_lshl_add_u32 v184, v9, 1, v2
	v_mov_b32_e32 v185, v1
	v_add_u32_e32 v203, 0, v7
	v_readlane_b32 s44, v245, 46
	s_mov_b32 s45, s0
	s_mov_b64 s[0:1], s[38:39]
	v_readlane_b32 s53, v246, 36
	v_readlane_b32 s54, v246, 37
	v_readlane_b32 s55, v246, 38
	s_barrier
	s_branch .LBB0_183

; __device__ __forceinline__ unsigned cvt_pk_bf16(float lo, float hi) { unsigned r; asm volatile("v_cvt_pk_bf16_f32 %0, %1, %2" : "=v"(r) : "v"(lo), "v"(hi)); return r; }
;     __device__ __forceinline__ void operator()(const f32x4 (&acc)[2][2][4][2], const Unit& u, int wr, int wc, int fr, int fq) const {
;     ...
;                     f32x4 v0 = acc[ai][bj][m][0] + bv[bj][0], v1 = acc[ai][bj][m][1] + bv[bj][1];
;                     const int cb = colt + bj * HALF;
;                     if (rot_wave && cb < 640) {
;                         const f32x4 t1 = v0, t2 = v1;
;                         v0 = t1 * cc[mm][0] - t2 * cc[mm][1]; v1 = t2 * cc[mm][0] + t1 * cc[mm][1];
;                     }
;                     if (cb < 512) { v0 = v0 * 0.125f; v1 = v1 * 0.125f; }
;                     u32x4 w; w.x = cvt_pk_bf16(v0[0], v0[1]); w.y = cvt_pk_bf16(v0[2], v0[3]); w.z = cvt_pk_bf16(v1[0], v1[1]); w.w = cvt_pk_bf16(v1[2], v1[3]);
;                     *(u32x4*)(rowp + bj * HALF) = w;
.LBB0_193:
	s_or_b64 exec, exec, s[0:1]
	s_waitcnt vmcnt(0)
	v_pk_add_f32 v[140:141], v[140:141], v[92:93]
	v_pk_add_f32 v[138:139], v[138:139], v[90:91]
	v_pk_add_f32 v[144:145], v[144:145], v[96:97]
	v_pk_add_f32 v[142:143], v[142:143], v[94:95]
	v_pk_mul_f32 v[216:217], v[138:139], v[154:155]
	v_pk_mul_f32 v[218:219], v[140:141], v[156:157]
	v_pk_mul_f32 v[212:213], v[138:139], v[158:159]
	v_pk_mul_f32 v[214:215], v[140:141], v[160:161]
	v_pk_fma_f32 v[218:219], v[144:145], v[160:161], v[218:219]
	v_pk_fma_f32 v[216:217], v[142:143], v[158:159], v[216:217]
	v_pk_fma_f32 v[214:215], v[144:145], v[156:157], v[214:215] neg_lo:[0,0,1] neg_hi:[0,0,1]
	v_pk_fma_f32 v[212:213], v[142:143], v[154:155], v[212:213] neg_lo:[0,0,1] neg_hi:[0,0,1]
	v_cndmask_b32_e64 v141, v141, v219, s[40:41]
	v_cndmask_b32_e64 v140, v140, v218, s[40:41]
	v_cndmask_b32_e64 v139, v139, v217, s[40:41]
	v_cndmask_b32_e64 v138, v138, v216, s[40:41]
	s_cmp_lt_i32 s44, 2
	v_ashrrev_i32_e32 v187, 31, v186
	v_mov_b64_e32 v[208:209], s[74:75]
	v_cndmask_b32_e64 v145, v145, v215, s[40:41]
	v_cndmask_b32_e64 v144, v144, v214, s[40:41]
	v_cndmask_b32_e64 v143, v143, v213, s[40:41]
	v_cndmask_b32_e64 v142, v142, v212, s[40:41]
	v_pk_mul_f32 v[216:217], v[140:141], s[28:29] op_sel_hi:[1,0]
	v_pk_mul_f32 v[218:219], v[138:139], s[28:29] op_sel_hi:[1,0]
	s_cselect_b64 s[42:43], -1, 0
	v_mad_i64_i32 v[210:211], s[0:1], v188, s85, v[208:209]
	v_lshlrev_b64 v[186:187], 1, v[186:187]
	v_pk_mul_f32 v[212:213], v[144:145], s[28:29] op_sel_hi:[1,0]
	v_pk_mul_f32 v[214:215], v[142:143], s[28:29] op_sel_hi:[1,0]
	v_cndmask_b32_e64 v189, v140, v216, s[42:43]
	v_cndmask_b32_e64 v141, v141, v217, s[42:43]
	v_cndmask_b32_e64 v140, v138, v218, s[42:43]
	v_lshl_add_u64 v[210:211], v[210:211], 0, v[186:187]
	v_cndmask_b32_e64 v144, v144, v212, s[42:43]
	v_cndmask_b32_e64 v145, v145, v213, s[42:43]
	v_cndmask_b32_e64 v142, v142, v214, s[42:43]
	v_cndmask_b32_e64 v143, v143, v215, s[42:43]
	v_cndmask_b32_e64 v212, v139, v219, s[42:43]
	v_cvt_pk_bf16_f32 v138, v142, v143
	v_cvt_pk_bf16_f32 v139, v144, v145
	v_cvt_pk_bf16_f32 v140, v140, v212
	v_cvt_pk_bf16_f32 v141, v189, v141
	v_pk_add_f32 v[132:133], v[132:133], v[76:77]
	v_pk_add_f32 v[130:131], v[130:131], v[74:75]
	ds_bpermute_b32 v138, v248, v138
	ds_bpermute_b32 v139, v248, v139
	ds_bpermute_b32 v140, v248, v140
	ds_bpermute_b32 v141, v248, v141
	v_lshl_add_u64 v[254:255], v[210:211], 0, v[252:253]
	s_waitcnt lgkmcnt(0)
	global_store_dwordx4 v[254:255], v[138:141], off
	v_pk_add_f32 v[136:137], v[136:137], v[80:81]
	v_pk_add_f32 v[134:135], v[134:135], v[78:79]
	v_pk_mul_f32 v[138:139], v[130:131], v[158:159]
	v_pk_mul_f32 v[140:141], v[132:133], v[160:161]
	v_pk_mul_f32 v[142:143], v[130:131], v[154:155]
	v_pk_mul_f32 v[144:145], v[132:133], v[156:157]
	v_pk_fma_f32 v[140:141], v[136:137], v[156:157], v[140:141] neg_lo:[0,0,1] neg_hi:[0,0,1]
	v_pk_fma_f32 v[138:139], v[134:135], v[154:155], v[138:139] neg_lo:[0,0,1] neg_hi:[0,0,1]
	v_pk_fma_f32 v[144:145], v[136:137], v[160:161], v[144:145]
	v_pk_fma_f32 v[142:143], v[134:135], v[158:159], v[142:143]
	v_cndmask_b32_e32 v137, v137, v141, vcc
	v_cndmask_b32_e32 v136, v136, v140, vcc
	v_cndmask_b32_e32 v135, v135, v139, vcc
	v_cndmask_b32_e32 v134, v134, v138, vcc
	v_cndmask_b32_e32 v133, v133, v145, vcc
	v_cndmask_b32_e32 v132, v132, v144, vcc
	v_cndmask_b32_e32 v131, v131, v143, vcc
	v_cndmask_b32_e32 v130, v130, v142, vcc
	s_cmpk_lt_i32 s16, 0x200
	v_pk_mul_f32 v[138:139], v[136:137], s[28:29] op_sel_hi:[1,0]
	v_pk_mul_f32 v[140:141], v[134:135], s[28:29] op_sel_hi:[1,0]
	v_pk_mul_f32 v[142:143], v[132:133], s[28:29] op_sel_hi:[1,0]
	v_pk_mul_f32 v[144:145], v[130:131], s[28:29] op_sel_hi:[1,0]
	s_cselect_b64 s[44:45], -1, 0
	v_cndmask_b32_e64 v136, v136, v138, s[44:45]
	v_cndmask_b32_e64 v137, v137, v139, s[44:45]
	v_cndmask_b32_e64 v134, v134, v140, s[44:45]
	v_cndmask_b32_e64 v135, v135, v141, s[44:45]
	v_cndmask_b32_e64 v138, v132, v142, s[44:45]
	v_cndmask_b32_e64 v133, v133, v143, s[44:45]
	v_cndmask_b32_e64 v132, v130, v144, s[44:45]
	v_cndmask_b32_e64 v139, v131, v145, s[44:45]
	v_cvt_pk_bf16_f32 v130, v134, v135
	v_cvt_pk_bf16_f32 v131, v136, v137
	v_cvt_pk_bf16_f32 v132, v132, v139
	v_cvt_pk_bf16_f32 v133, v138, v133
	ds_bpermute_b32 v130, v248, v130
	ds_bpermute_b32 v131, v248, v131
	ds_bpermute_b32 v132, v248, v132
	ds_bpermute_b32 v133, v248, v133
	v_lshl_add_u64 v[254:255], v[210:211], 0, v[252:253]
	s_waitcnt lgkmcnt(0)
; __device__ __forceinline__ unsigned cvt_pk_bf16(float lo, float hi) { unsigned r; asm volatile("v_cvt_pk_bf16_f32 %0, %1, %2" : "=v"(r) : "v"(lo), "v"(hi)); return r; }
;     __device__ __forceinline__ void operator()(const f32x4 (&acc)[2][2][4][2], const Unit& u, int wr, int wc, int fr, int fq) const {
;     ...
;             if (rot_wave && fq < 2) {
; #pragma unroll
;                 for (int mm = 0; mm < 2; ++mm) { const float* cr = cs + (size_t)(row0 + ai * HALF + (2 * mh + mm) * 16) * 16 + 4 * fq;
;                     cc[mm][0] = *(const f32x4*)(cr); cc[mm][1] = *(const f32x4*)(cr + 8); }
;             }
; #pragma unroll
;             for (int mm = 0; mm < 2; ++mm) {
;                 const int m = 2 * mh + mm;
;                 const int row = row0 + ai * HALF + m * 16;
;                 bf16_t* rowp = O + (size_t)row * INW + col0;
; #pragma unroll
;                 for (int bj = 0; bj < 2; ++bj) {
;                     f32x4 v0 = acc[ai][bj][m][0] + bv[bj][0], v1 = acc[ai][bj][m][1] + bv[bj][1];
;                     const int cb = colt + bj * HALF;
;                     if (rot_wave && cb < 640) {
;                         const f32x4 t1 = v0, t2 = v1;
;                         v0 = t1 * cc[mm][0] - t2 * cc[mm][1]; v1 = t2 * cc[mm][0] + t1 * cc[mm][1];
;                     }
;                     if (cb < 512) { v0 = v0 * 0.125f; v1 = v1 * 0.125f; }
;                     u32x4 w; w.x = cvt_pk_bf16(v0[0], v0[1]); w.y = cvt_pk_bf16(v0[2], v0[3]); w.z = cvt_pk_bf16(v1[0], v1[1]); w.w = cvt_pk_bf16(v1[2], v1[3]);
;                     *(u32x4*)(rowp + bj * HALF) = w;
	global_store_dwordx4 v[254:255], v[130:133], off offset:256
	v_pk_add_f32 v[124:125], v[124:125], v[92:93]
	v_pk_add_f32 v[122:123], v[122:123], v[90:91]
	v_mad_u64_u32 v[130:131], s[0:1], v190, s85, v[208:209]
	v_mov_b32_e32 v132, v131
	v_mad_u64_u32 v[132:133], s[0:1], v191, s85, v[132:133]
	v_pk_add_f32 v[128:129], v[128:129], v[96:97]
	v_pk_add_f32 v[126:127], v[126:127], v[94:95]
	v_pk_mul_f32 v[134:135], v[124:125], v[148:149]
	v_pk_mul_f32 v[136:137], v[122:123], v[150:151]
	v_pk_mul_f32 v[138:139], v[124:125], v[152:153]
	v_mov_b32_e32 v131, v132
	v_pk_mul_f32 v[132:133], v[122:123], v[146:147]
	v_pk_fma_f32 v[134:135], v[128:129], v[152:153], v[134:135] neg_lo:[0,0,1] neg_hi:[0,0,1]
	v_pk_fma_f32 v[138:139], v[128:129], v[148:149], v[138:139]
	v_pk_fma_f32 v[136:137], v[126:127], v[146:147], v[136:137]
	v_pk_fma_f32 v[132:133], v[126:127], v[150:151], v[132:133] neg_lo:[0,0,1] neg_hi:[0,0,1]
	v_cndmask_b32_e64 v129, v129, v135, s[40:41]
	v_cndmask_b32_e64 v128, v128, v134, s[40:41]
	v_cndmask_b32_e64 v125, v125, v139, s[40:41]
	v_cndmask_b32_e64 v124, v124, v138, s[40:41]
	v_cndmask_b32_e64 v123, v123, v137, s[40:41]
	v_cndmask_b32_e64 v122, v122, v136, s[40:41]
	v_cndmask_b32_e64 v127, v127, v133, s[40:41]
	v_cndmask_b32_e64 v126, v126, v132, s[40:41]
	v_pk_mul_f32 v[132:133], v[128:129], s[28:29] op_sel_hi:[1,0]
	v_pk_mul_f32 v[136:137], v[124:125], s[28:29] op_sel_hi:[1,0]
	v_pk_mul_f32 v[138:139], v[122:123], s[28:29] op_sel_hi:[1,0]
	v_pk_mul_f32 v[134:135], v[126:127], s[28:29] op_sel_hi:[1,0]
	v_cndmask_b32_e64 v128, v128, v132, s[42:43]
	v_cndmask_b32_e64 v132, v124, v136, s[42:43]
	v_cndmask_b32_e64 v125, v125, v137, s[42:43]
	v_cndmask_b32_e64 v124, v122, v138, s[42:43]
	v_lshl_add_u64 v[130:131], v[130:131], 0, v[186:187]
	v_cndmask_b32_e64 v129, v129, v133, s[42:43]
	v_cndmask_b32_e64 v126, v126, v134, s[42:43]
	v_cndmask_b32_e64 v127, v127, v135, s[42:43]
	v_cndmask_b32_e64 v133, v123, v139, s[42:43]
	v_cvt_pk_bf16_f32 v122, v126, v127
	v_cvt_pk_bf16_f32 v123, v128, v129
	v_cvt_pk_bf16_f32 v124, v124, v133
	v_cvt_pk_bf16_f32 v125, v132, v125
	v_pk_add_f32 v[116:117], v[116:117], v[76:77]
	v_pk_add_f32 v[114:115], v[114:115], v[74:75]
	ds_bpermute_b32 v122, v248, v122
	ds_bpermute_b32 v123, v248, v123
	ds_bpermute_b32 v124, v248, v124
	ds_bpermute_b32 v125, v248, v125
	v_lshl_add_u64 v[254:255], v[130:131], 0, v[252:253]
	s_waitcnt lgkmcnt(0)
	global_store_dwordx4 v[254:255], v[122:125], off
	v_pk_add_f32 v[120:121], v[120:121], v[80:81]
	v_pk_add_f32 v[118:119], v[118:119], v[78:79]
	v_pk_mul_f32 v[124:125], v[116:117], v[148:149]
	v_pk_mul_f32 v[126:127], v[114:115], v[150:151]
	v_pk_mul_f32 v[128:129], v[116:117], v[152:153]
	v_pk_mul_f32 v[122:123], v[114:115], v[146:147]
	v_pk_fma_f32 v[124:125], v[120:121], v[152:153], v[124:125] neg_lo:[0,0,1] neg_hi:[0,0,1]
	v_pk_fma_f32 v[128:129], v[120:121], v[148:149], v[128:129]
	v_pk_fma_f32 v[126:127], v[118:119], v[146:147], v[126:127]
	v_pk_fma_f32 v[122:123], v[118:119], v[150:151], v[122:123] neg_lo:[0,0,1] neg_hi:[0,0,1]
	v_cndmask_b32_e32 v121, v121, v125, vcc
	v_cndmask_b32_e32 v120, v120, v124, vcc
	v_cndmask_b32_e32 v117, v117, v129, vcc
	v_cndmask_b32_e32 v116, v116, v128, vcc
	v_cndmask_b32_e32 v115, v115, v127, vcc
	v_cndmask_b32_e32 v114, v114, v126, vcc
	v_cndmask_b32_e32 v119, v119, v123, vcc
	v_cndmask_b32_e32 v118, v118, v122, vcc
	v_pk_mul_f32 v[122:123], v[120:121], s[28:29] op_sel_hi:[1,0]
	v_pk_mul_f32 v[126:127], v[116:117], s[28:29] op_sel_hi:[1,0]
	v_pk_mul_f32 v[128:129], v[114:115], s[28:29] op_sel_hi:[1,0]
	v_pk_mul_f32 v[124:125], v[118:119], s[28:29] op_sel_hi:[1,0]
	v_cndmask_b32_e64 v120, v120, v122, s[44:45]
	v_cndmask_b32_e64 v122, v116, v126, s[44:45]
	v_cndmask_b32_e64 v117, v117, v127, s[44:45]
	v_cndmask_b32_e64 v116, v114, v128, s[44:45]
	v_cndmask_b32_e64 v121, v121, v123, s[44:45]
	v_cndmask_b32_e64 v118, v118, v124, s[44:45]
	v_cndmask_b32_e64 v119, v119, v125, s[44:45]
	v_cndmask_b32_e64 v123, v115, v129, s[44:45]
	v_cvt_pk_bf16_f32 v114, v118, v119
	v_cvt_pk_bf16_f32 v115, v120, v121
	v_cvt_pk_bf16_f32 v116, v116, v123
	v_cvt_pk_bf16_f32 v117, v122, v117
	ds_bpermute_b32 v114, v248, v114
	ds_bpermute_b32 v115, v248, v115
	ds_bpermute_b32 v116, v248, v116
	ds_bpermute_b32 v117, v248, v117
	v_lshl_add_u64 v[254:255], v[130:131], 0, v[252:253]
	s_waitcnt lgkmcnt(0)
	global_store_dwordx4 v[254:255], v[114:117], off offset:256
	v_or_b32_e32 v130, 48, v188
	s_and_saveexec_b64 s[0:1], s[58:59]
	s_xor_b64 s[0:1], exec, s[0:1]
	v_ashrrev_i32_e32 v131, 31, v130
	s_or_saveexec_b64 s[0:1], s[0:1]
	v_or_b32_e32 v132, 32, v188
	v_ashrrev_i32_e32 v133, 31, v132
	v_mov_b32_e32 v122, 1.0
	v_mov_b32_e32 v114, 0
	v_mov_b32_e32 v115, 0
	v_mov_b32_e32 v116, 0
	v_mov_b32_e32 v117, 0
	v_mov_b32_e32 v123, 1.0
	v_mov_b32_e32 v124, 1.0
	v_mov_b32_e32 v125, 1.0
	v_mov_b32_e32 v126, 0
	v_mov_b32_e32 v127, 0
	v_mov_b32_e32 v128, 0
	v_mov_b32_e32 v129, 0
	v_mov_b32_e32 v118, 1.0
	v_mov_b32_e32 v119, 1.0
	v_mov_b32_e32 v120, 1.0
	v_mov_b32_e32 v121, 1.0
	s_xor_b64 exec, exec, s[0:1]
	s_cbranch_execz .LBB0_197
	v_lshlrev_b64 v[114:115], 6, v[132:133]
	v_lshl_add_u64 v[114:115], v[180:181], 0, v[114:115]
	v_ashrrev_i32_e32 v131, 31, v130
	global_load_dwordx4 v[122:125], v[114:115], off
	global_load_dwordx4 v[126:129], v[114:115], off offset:32
	v_lshlrev_b64 v[114:115], 6, v[130:131]
	v_lshl_add_u64 v[114:115], v[180:181], 0, v[114:115]
	global_load_dwordx4 v[118:121], v[114:115], off
	s_nop 0
	global_load_dwordx4 v[114:117], v[114:115], off offset:32
; __device__ __forceinline__ unsigned cvt_pk_bf16(float lo, float hi) { unsigned r; asm volatile("v_cvt_pk_bf16_f32 %0, %1, %2" : "=v"(r) : "v"(lo), "v"(hi)); return r; }
;     __device__ __forceinline__ void operator()(const f32x4 (&acc)[2][2][4][2], const Unit& u, int wr, int wc, int fr, int fq) const {
;     ...
;             if (rot_wave && fq < 2) {
; #pragma unroll
;                 for (int mm = 0; mm < 2; ++mm) { const float* cr = cs + (size_t)(row0 + ai * HALF + (2 * mh + mm) * 16) * 16 + 4 * fq;
;                     cc[mm][0] = *(const f32x4*)(cr); cc[mm][1] = *(const f32x4*)(cr + 8); }
;             }
; #pragma unroll
;             for (int mm = 0; mm < 2; ++mm) {
;                 const int m = 2 * mh + mm;
;                 const int row = row0 + ai * HALF + m * 16;
;                 bf16_t* rowp = O + (size_t)row * INW + col0;
; #pragma unroll
;                 for (int bj = 0; bj < 2; ++bj) {
;                     f32x4 v0 = acc[ai][bj][m][0] + bv[bj][0], v1 = acc[ai][bj][m][1] + bv[bj][1];
;                     const int cb = colt + bj * HALF;
;                     if (rot_wave && cb < 640) {
;                         const f32x4 t1 = v0, t2 = v1;
;                         v0 = t1 * cc[mm][0] - t2 * cc[mm][1]; v1 = t2 * cc[mm][0] + t1 * cc[mm][1];
;                     }
;                     if (cb < 512) { v0 = v0 * 0.125f; v1 = v1 * 0.125f; }
;                     u32x4 w; w.x = cvt_pk_bf16(v0[0], v0[1]); w.y = cvt_pk_bf16(v0[2], v0[3]); w.z = cvt_pk_bf16(v1[0], v1[1]); w.w = cvt_pk_bf16(v1[2], v1[3]);
;                     *(u32x4*)(rowp + bj * HALF) = w;
.LBB0_197:
	s_or_b64 exec, exec, s[0:1]
	v_pk_add_f32 v[108:109], v[108:109], v[92:93]
	v_pk_add_f32 v[106:107], v[106:107], v[90:91]
	v_pk_add_f32 v[112:113], v[112:113], v[96:97]
	v_pk_add_f32 v[110:111], v[110:111], v[94:95]
	s_waitcnt vmcnt(2)
	v_pk_mul_f32 v[138:139], v[108:109], v[128:129]
	v_pk_mul_f32 v[140:141], v[106:107], v[122:123]
	v_pk_mul_f32 v[142:143], v[108:109], v[124:125]
	v_pk_mul_f32 v[136:137], v[106:107], v[126:127]
	v_pk_fma_f32 v[138:139], v[112:113], v[124:125], v[138:139] neg_lo:[0,0,1] neg_hi:[0,0,1]
	v_pk_fma_f32 v[142:143], v[112:113], v[128:129], v[142:143]
	v_pk_fma_f32 v[140:141], v[110:111], v[126:127], v[140:141]
	v_pk_fma_f32 v[136:137], v[110:111], v[122:123], v[136:137] neg_lo:[0,0,1] neg_hi:[0,0,1]
	v_cndmask_b32_e64 v113, v113, v139, s[40:41]
	v_cndmask_b32_e64 v112, v112, v138, s[40:41]
	v_cndmask_b32_e64 v109, v109, v143, s[40:41]
	v_cndmask_b32_e64 v108, v108, v142, s[40:41]
	v_cndmask_b32_e64 v107, v107, v141, s[40:41]
	v_cndmask_b32_e64 v106, v106, v140, s[40:41]
	v_mov_b64_e32 v[134:135], s[74:75]
	v_cndmask_b32_e64 v111, v111, v137, s[40:41]
	v_cndmask_b32_e64 v110, v110, v136, s[40:41]
	v_pk_mul_f32 v[136:137], v[112:113], s[28:29] op_sel_hi:[1,0]
	v_pk_mul_f32 v[140:141], v[108:109], s[28:29] op_sel_hi:[1,0]
	v_pk_mul_f32 v[142:143], v[106:107], s[28:29] op_sel_hi:[1,0]
	v_mad_i64_i32 v[132:133], s[0:1], v132, s85, v[134:135]
	v_pk_mul_f32 v[138:139], v[110:111], s[28:29] op_sel_hi:[1,0]
	v_cndmask_b32_e64 v112, v112, v136, s[42:43]
	v_cndmask_b32_e64 v136, v108, v140, s[42:43]
	v_cndmask_b32_e64 v109, v109, v141, s[42:43]
	v_cndmask_b32_e64 v108, v106, v142, s[42:43]
	v_lshl_add_u64 v[132:133], v[132:133], 0, v[186:187]
	v_cndmask_b32_e64 v113, v113, v137, s[42:43]
	v_cndmask_b32_e64 v110, v110, v138, s[42:43]
	v_cndmask_b32_e64 v111, v111, v139, s[42:43]
	v_cndmask_b32_e64 v137, v107, v143, s[42:43]
	v_cvt_pk_bf16_f32 v106, v110, v111
	v_cvt_pk_bf16_f32 v107, v112, v113
	v_cvt_pk_bf16_f32 v108, v108, v137
	v_cvt_pk_bf16_f32 v109, v136, v109
	v_pk_add_f32 v[100:101], v[100:101], v[76:77]
	v_pk_add_f32 v[98:99], v[98:99], v[74:75]
	ds_bpermute_b32 v106, v248, v106
	ds_bpermute_b32 v107, v248, v107
	ds_bpermute_b32 v108, v248, v108
	ds_bpermute_b32 v109, v248, v109
	v_lshl_add_u64 v[254:255], v[132:133], 0, v[252:253]
	s_waitcnt lgkmcnt(0)
	global_store_dwordx4 v[254:255], v[106:109], off
	v_pk_add_f32 v[104:105], v[104:105], v[80:81]
	v_pk_add_f32 v[102:103], v[102:103], v[78:79]
	v_pk_mul_f32 v[106:107], v[98:99], v[126:127]
	v_pk_mul_f32 v[108:109], v[100:101], v[128:129]
	v_pk_mul_f32 v[110:111], v[98:99], v[122:123]
	v_pk_mul_f32 v[112:113], v[100:101], v[124:125]
	v_pk_fma_f32 v[108:109], v[104:105], v[124:125], v[108:109] neg_lo:[0,0,1] neg_hi:[0,0,1]
	v_pk_fma_f32 v[106:107], v[102:103], v[122:123], v[106:107] neg_lo:[0,0,1] neg_hi:[0,0,1]
	v_pk_fma_f32 v[112:113], v[104:105], v[128:129], v[112:113]
	v_pk_fma_f32 v[110:111], v[102:103], v[126:127], v[110:111]
	v_cndmask_b32_e32 v105, v105, v109, vcc
	v_cndmask_b32_e32 v104, v104, v108, vcc
	v_cndmask_b32_e32 v103, v103, v107, vcc
	v_cndmask_b32_e32 v102, v102, v106, vcc
	v_cndmask_b32_e32 v101, v101, v113, vcc
	v_cndmask_b32_e32 v100, v100, v112, vcc
	v_cndmask_b32_e32 v99, v99, v111, vcc
	v_cndmask_b32_e32 v98, v98, v110, vcc
	v_pk_mul_f32 v[106:107], v[104:105], s[28:29] op_sel_hi:[1,0]
	v_pk_mul_f32 v[108:109], v[102:103], s[28:29] op_sel_hi:[1,0]
	v_pk_mul_f32 v[110:111], v[100:101], s[28:29] op_sel_hi:[1,0]
	v_pk_mul_f32 v[112:113], v[98:99], s[28:29] op_sel_hi:[1,0]
	v_cndmask_b32_e64 v104, v104, v106, s[44:45]
	v_cndmask_b32_e64 v105, v105, v107, s[44:45]
	v_cndmask_b32_e64 v102, v102, v108, s[44:45]
	v_cndmask_b32_e64 v103, v103, v109, s[44:45]
	v_cndmask_b32_e64 v106, v100, v110, s[44:45]
	v_cndmask_b32_e64 v101, v101, v111, s[44:45]
	v_cndmask_b32_e64 v100, v98, v112, s[44:45]
	v_cndmask_b32_e64 v107, v99, v113, s[44:45]
	v_cvt_pk_bf16_f32 v98, v102, v103
	v_cvt_pk_bf16_f32 v99, v104, v105
	v_cvt_pk_bf16_f32 v100, v100, v107
	v_cvt_pk_bf16_f32 v101, v106, v101
	ds_bpermute_b32 v98, v248, v98
	ds_bpermute_b32 v99, v248, v99
	ds_bpermute_b32 v100, v248, v100
	ds_bpermute_b32 v101, v248, v101
	v_lshl_add_u64 v[254:255], v[132:133], 0, v[252:253]
	s_waitcnt lgkmcnt(0)
	global_store_dwordx4 v[254:255], v[98:101], off offset:256
	v_pk_add_f32 v[84:85], v[84:85], v[92:93]
	v_pk_add_f32 v[82:83], v[82:83], v[90:91]
	v_mad_u64_u32 v[98:99], s[0:1], v130, s85, v[134:135]
	v_mov_b32_e32 v100, v99
	v_mad_u64_u32 v[100:101], s[0:1], v131, s85, v[100:101]
	v_pk_add_f32 v[88:89], v[88:89], v[96:97]
	v_pk_add_f32 v[86:87], v[86:87], v[94:95]
	s_waitcnt vmcnt(2)
	v_pk_mul_f32 v[102:103], v[84:85], v[116:117]
	v_pk_mul_f32 v[104:105], v[82:83], v[118:119]
	v_pk_mul_f32 v[106:107], v[84:85], v[120:121]
	v_mov_b32_e32 v99, v100
	v_pk_mul_f32 v[100:101], v[82:83], v[114:115]
	v_pk_fma_f32 v[102:103], v[88:89], v[120:121], v[102:103] neg_lo:[0,0,1] neg_hi:[0,0,1]
	v_pk_fma_f32 v[106:107], v[88:89], v[116:117], v[106:107]
	v_pk_fma_f32 v[104:105], v[86:87], v[114:115], v[104:105]
	v_pk_fma_f32 v[100:101], v[86:87], v[118:119], v[100:101] neg_lo:[0,0,1] neg_hi:[0,0,1]
	v_cndmask_b32_e64 v89, v89, v103, s[40:41]
	v_cndmask_b32_e64 v88, v88, v102, s[40:41]
	v_cndmask_b32_e64 v85, v85, v107, s[40:41]
	v_cndmask_b32_e64 v84, v84, v106, s[40:41]
	v_cndmask_b32_e64 v83, v83, v105, s[40:41]
	v_cndmask_b32_e64 v82, v82, v104, s[40:41]
	v_cndmask_b32_e64 v87, v87, v101, s[40:41]
	v_cndmask_b32_e64 v86, v86, v100, s[40:41]
	v_pk_mul_f32 v[100:101], v[88:89], s[28:29] op_sel_hi:[1,0]
	v_pk_mul_f32 v[104:105], v[84:85], s[28:29] op_sel_hi:[1,0]
	v_pk_mul_f32 v[106:107], v[82:83], s[28:29] op_sel_hi:[1,0]
	v_pk_mul_f32 v[102:103], v[86:87], s[28:29] op_sel_hi:[1,0]
	v_cndmask_b32_e64 v88, v88, v100, s[42:43]
	v_cndmask_b32_e64 v100, v84, v104, s[42:43]
	v_cndmask_b32_e64 v85, v85, v105, s[42:43]
	v_cndmask_b32_e64 v84, v82, v106, s[42:43]
	v_lshl_add_u64 v[98:99], v[98:99], 0, v[186:187]
	v_cndmask_b32_e64 v89, v89, v101, s[42:43]
	v_cndmask_b32_e64 v86, v86, v102, s[42:43]
	v_cndmask_b32_e64 v87, v87, v103, s[42:43]
	v_cndmask_b32_e64 v101, v83, v107, s[42:43]
	v_cvt_pk_bf16_f32 v82, v86, v87
	v_cvt_pk_bf16_f32 v83, v88, v89
	v_cvt_pk_bf16_f32 v84, v84, v101
	v_cvt_pk_bf16_f32 v85, v100, v85
	v_pk_add_f32 v[68:69], v[68:69], v[76:77]
	v_pk_add_f32 v[66:67], v[66:67], v[74:75]
	ds_bpermute_b32 v82, v248, v82
	ds_bpermute_b32 v83, v248, v83
	ds_bpermute_b32 v84, v248, v84
	ds_bpermute_b32 v85, v248, v85
	v_lshl_add_u64 v[254:255], v[98:99], 0, v[252:253]
	s_waitcnt lgkmcnt(0)
; __device__ __forceinline__ unsigned cvt_pk_bf16(float lo, float hi) { unsigned r; asm volatile("v_cvt_pk_bf16_f32 %0, %1, %2" : "=v"(r) : "v"(lo), "v"(hi)); return r; }
;     __device__ __forceinline__ void operator()(const f32x4 (&acc)[2][2][4][2], const Unit& u, int wr, int wc, int fr, int fq) const {
;     ...
;             if (rot_wave && fq < 2) {
; #pragma unroll
;                 for (int mm = 0; mm < 2; ++mm) { const float* cr = cs + (size_t)(row0 + ai * HALF + (2 * mh + mm) * 16) * 16 + 4 * fq;
;                     cc[mm][0] = *(const f32x4*)(cr); cc[mm][1] = *(const f32x4*)(cr + 8); }
;             }
; #pragma unroll
;             for (int mm = 0; mm < 2; ++mm) {
;                 const int m = 2 * mh + mm;
;                 const int row = row0 + ai * HALF + m * 16;
;                 bf16_t* rowp = O + (size_t)row * INW + col0;
; #pragma unroll
;                 for (int bj = 0; bj < 2; ++bj) {
;                     f32x4 v0 = acc[ai][bj][m][0] + bv[bj][0], v1 = acc[ai][bj][m][1] + bv[bj][1];
;                     const int cb = colt + bj * HALF;
;                     if (rot_wave && cb < 640) {
;                         const f32x4 t1 = v0, t2 = v1;
;                         v0 = t1 * cc[mm][0] - t2 * cc[mm][1]; v1 = t2 * cc[mm][0] + t1 * cc[mm][1];
;                     }
;                     if (cb < 512) { v0 = v0 * 0.125f; v1 = v1 * 0.125f; }
;                     u32x4 w; w.x = cvt_pk_bf16(v0[0], v0[1]); w.y = cvt_pk_bf16(v0[2], v0[3]); w.z = cvt_pk_bf16(v1[0], v1[1]); w.w = cvt_pk_bf16(v1[2], v1[3]);
;                     *(u32x4*)(rowp + bj * HALF) = w;
	global_store_dwordx4 v[254:255], v[82:85], off
	v_pk_add_f32 v[72:73], v[72:73], v[80:81]
	v_pk_add_f32 v[70:71], v[70:71], v[78:79]
	v_pk_mul_f32 v[84:85], v[68:69], v[116:117]
	v_pk_mul_f32 v[86:87], v[66:67], v[118:119]
	v_pk_mul_f32 v[88:89], v[68:69], v[120:121]
	v_pk_mul_f32 v[82:83], v[66:67], v[114:115]
	v_pk_fma_f32 v[84:85], v[72:73], v[120:121], v[84:85] neg_lo:[0,0,1] neg_hi:[0,0,1]
	v_pk_fma_f32 v[88:89], v[72:73], v[116:117], v[88:89]
	v_pk_fma_f32 v[86:87], v[70:71], v[114:115], v[86:87]
	v_pk_fma_f32 v[82:83], v[70:71], v[118:119], v[82:83] neg_lo:[0,0,1] neg_hi:[0,0,1]
	v_cndmask_b32_e32 v73, v73, v85, vcc
	v_cndmask_b32_e32 v72, v72, v84, vcc
	v_cndmask_b32_e32 v69, v69, v89, vcc
	v_cndmask_b32_e32 v68, v68, v88, vcc
	v_cndmask_b32_e32 v67, v67, v87, vcc
	v_cndmask_b32_e32 v66, v66, v86, vcc
	v_cndmask_b32_e32 v71, v71, v83, vcc
	v_cndmask_b32_e32 v70, v70, v82, vcc
	v_pk_mul_f32 v[82:83], v[72:73], s[28:29] op_sel_hi:[1,0]
	v_pk_mul_f32 v[86:87], v[68:69], s[28:29] op_sel_hi:[1,0]
	v_pk_mul_f32 v[88:89], v[66:67], s[28:29] op_sel_hi:[1,0]
	v_pk_mul_f32 v[84:85], v[70:71], s[28:29] op_sel_hi:[1,0]
	v_cndmask_b32_e64 v72, v72, v82, s[44:45]
	v_cndmask_b32_e64 v82, v68, v86, s[44:45]
	v_cndmask_b32_e64 v69, v69, v87, s[44:45]
	v_cndmask_b32_e64 v68, v66, v88, s[44:45]
	v_cndmask_b32_e64 v73, v73, v83, s[44:45]
	v_cndmask_b32_e64 v70, v70, v84, s[44:45]
	v_cndmask_b32_e64 v71, v71, v85, s[44:45]
	v_cndmask_b32_e64 v83, v67, v89, s[44:45]
	v_cvt_pk_bf16_f32 v66, v70, v71
	v_cvt_pk_bf16_f32 v67, v72, v73
	v_cvt_pk_bf16_f32 v68, v68, v83
	v_cvt_pk_bf16_f32 v69, v82, v69
	ds_bpermute_b32 v66, v248, v66
	ds_bpermute_b32 v67, v248, v67
	ds_bpermute_b32 v68, v248, v68
	ds_bpermute_b32 v69, v248, v69
	v_lshl_add_u64 v[254:255], v[98:99], 0, v[252:253]
	s_waitcnt lgkmcnt(0)
	global_store_dwordx4 v[254:255], v[66:69], off offset:256
	v_add_u32_e32 v98, 0x90, v188
	s_and_saveexec_b64 s[0:1], s[58:59]
	s_xor_b64 s[0:1], exec, s[0:1]
	v_ashrrev_i32_e32 v99, 31, v98
	s_or_saveexec_b64 s[0:1], s[0:1]
	v_add_u32_e32 v100, 0x80, v188
	v_ashrrev_i32_e32 v101, 31, v100
	v_mov_b32_e32 v82, 1.0
	v_mov_b32_e32 v66, 0
	v_mov_b32_e32 v67, 0
	v_mov_b32_e32 v68, 0
	v_mov_b32_e32 v69, 0
	v_mov_b32_e32 v83, 1.0
	v_mov_b32_e32 v84, 1.0
	v_mov_b32_e32 v85, 1.0
	v_mov_b32_e32 v86, 0
	v_mov_b32_e32 v87, 0
	v_mov_b32_e32 v88, 0
	v_mov_b32_e32 v89, 0
	v_mov_b32_e32 v70, 1.0
	v_mov_b32_e32 v71, 1.0
	v_mov_b32_e32 v72, 1.0
	v_mov_b32_e32 v73, 1.0
	s_xor_b64 exec, exec, s[0:1]
	s_cbranch_execz .LBB0_201
	v_lshlrev_b64 v[66:67], 6, v[100:101]
	v_lshl_add_u64 v[66:67], v[180:181], 0, v[66:67]
	v_ashrrev_i32_e32 v99, 31, v98
	global_load_dwordx4 v[82:85], v[66:67], off
	global_load_dwordx4 v[86:89], v[66:67], off offset:32
	v_lshlrev_b64 v[66:67], 6, v[98:99]
	v_lshl_add_u64 v[66:67], v[180:181], 0, v[66:67]
	global_load_dwordx4 v[70:73], v[66:67], off
	s_nop 0
	global_load_dwordx4 v[66:69], v[66:67], off offset:32
.LBB0_201:
	s_or_b64 exec, exec, s[0:1]
	v_pk_add_f32 v[60:61], v[60:61], v[92:93]
	v_pk_add_f32 v[58:59], v[58:59], v[90:91]
	v_pk_add_f32 v[64:65], v[64:65], v[96:97]
	v_pk_add_f32 v[62:63], v[62:63], v[94:95]
	s_waitcnt vmcnt(2)
	v_pk_mul_f32 v[106:107], v[60:61], v[88:89]
	v_pk_mul_f32 v[108:109], v[58:59], v[82:83]
	v_pk_mul_f32 v[110:111], v[60:61], v[84:85]
	v_pk_mul_f32 v[104:105], v[58:59], v[86:87]
	v_pk_fma_f32 v[106:107], v[64:65], v[84:85], v[106:107] neg_lo:[0,0,1] neg_hi:[0,0,1]
	v_pk_fma_f32 v[110:111], v[64:65], v[88:89], v[110:111]
	v_pk_fma_f32 v[108:109], v[62:63], v[86:87], v[108:109]
	v_pk_fma_f32 v[104:105], v[62:63], v[82:83], v[104:105] neg_lo:[0,0,1] neg_hi:[0,0,1]
	v_cndmask_b32_e64 v65, v65, v107, s[40:41]
	v_cndmask_b32_e64 v64, v64, v106, s[40:41]
	v_cndmask_b32_e64 v61, v61, v111, s[40:41]
	v_cndmask_b32_e64 v60, v60, v110, s[40:41]
	v_cndmask_b32_e64 v59, v59, v109, s[40:41]
	v_cndmask_b32_e64 v58, v58, v108, s[40:41]
	v_mov_b64_e32 v[102:103], s[74:75]
	v_cndmask_b32_e64 v63, v63, v105, s[40:41]
	v_cndmask_b32_e64 v62, v62, v104, s[40:41]
	v_pk_mul_f32 v[104:105], v[64:65], s[28:29] op_sel_hi:[1,0]
	v_pk_mul_f32 v[108:109], v[60:61], s[28:29] op_sel_hi:[1,0]
	v_pk_mul_f32 v[110:111], v[58:59], s[28:29] op_sel_hi:[1,0]
	v_mad_i64_i32 v[100:101], s[0:1], v100, s85, v[102:103]
	v_pk_mul_f32 v[106:107], v[62:63], s[28:29] op_sel_hi:[1,0]
	v_cndmask_b32_e64 v64, v64, v104, s[42:43]
	v_cndmask_b32_e64 v104, v60, v108, s[42:43]
	v_cndmask_b32_e64 v61, v61, v109, s[42:43]
	v_cndmask_b32_e64 v60, v58, v110, s[42:43]
	v_lshl_add_u64 v[100:101], v[100:101], 0, v[186:187]
	v_cndmask_b32_e64 v65, v65, v105, s[42:43]
	v_cndmask_b32_e64 v62, v62, v106, s[42:43]
	v_cndmask_b32_e64 v63, v63, v107, s[42:43]
	v_cndmask_b32_e64 v105, v59, v111, s[42:43]
	v_cvt_pk_bf16_f32 v58, v62, v63
	v_cvt_pk_bf16_f32 v59, v64, v65
	v_cvt_pk_bf16_f32 v60, v60, v105
	v_cvt_pk_bf16_f32 v61, v104, v61
	v_pk_add_f32 v[52:53], v[52:53], v[76:77]
	v_pk_add_f32 v[50:51], v[50:51], v[74:75]
	ds_bpermute_b32 v58, v248, v58
	ds_bpermute_b32 v59, v248, v59
	ds_bpermute_b32 v60, v248, v60
	ds_bpermute_b32 v61, v248, v61
	v_lshl_add_u64 v[254:255], v[100:101], 0, v[252:253]
	s_waitcnt lgkmcnt(0)
; __device__ __forceinline__ unsigned cvt_pk_bf16(float lo, float hi) { unsigned r; asm volatile("v_cvt_pk_bf16_f32 %0, %1, %2" : "=v"(r) : "v"(lo), "v"(hi)); return r; }
;     __device__ __forceinline__ void operator()(const f32x4 (&acc)[2][2][4][2], const Unit& u, int wr, int wc, int fr, int fq) const {
;     ...
;             if (rot_wave && fq < 2) {
; #pragma unroll
;                 for (int mm = 0; mm < 2; ++mm) { const float* cr = cs + (size_t)(row0 + ai * HALF + (2 * mh + mm) * 16) * 16 + 4 * fq;
;                     cc[mm][0] = *(const f32x4*)(cr); cc[mm][1] = *(const f32x4*)(cr + 8); }
;             }
; #pragma unroll
;             for (int mm = 0; mm < 2; ++mm) {
;                 const int m = 2 * mh + mm;
;                 const int row = row0 + ai * HALF + m * 16;
;                 bf16_t* rowp = O + (size_t)row * INW + col0;
; #pragma unroll
;                 for (int bj = 0; bj < 2; ++bj) {
;                     f32x4 v0 = acc[ai][bj][m][0] + bv[bj][0], v1 = acc[ai][bj][m][1] + bv[bj][1];
;                     const int cb = colt + bj * HALF;
;                     if (rot_wave && cb < 640) {
;                         const f32x4 t1 = v0, t2 = v1;
;                         v0 = t1 * cc[mm][0] - t2 * cc[mm][1]; v1 = t2 * cc[mm][0] + t1 * cc[mm][1];
;                     }
;                     if (cb < 512) { v0 = v0 * 0.125f; v1 = v1 * 0.125f; }
;                     u32x4 w; w.x = cvt_pk_bf16(v0[0], v0[1]); w.y = cvt_pk_bf16(v0[2], v0[3]); w.z = cvt_pk_bf16(v1[0], v1[1]); w.w = cvt_pk_bf16(v1[2], v1[3]);
;                     *(u32x4*)(rowp + bj * HALF) = w;
	global_store_dwordx4 v[254:255], v[58:61], off
	v_pk_add_f32 v[56:57], v[56:57], v[80:81]
	v_pk_add_f32 v[54:55], v[54:55], v[78:79]
	v_pk_mul_f32 v[58:59], v[50:51], v[86:87]
	v_pk_mul_f32 v[60:61], v[52:53], v[88:89]
	v_pk_mul_f32 v[62:63], v[50:51], v[82:83]
	v_pk_mul_f32 v[64:65], v[52:53], v[84:85]
	v_pk_fma_f32 v[60:61], v[56:57], v[84:85], v[60:61] neg_lo:[0,0,1] neg_hi:[0,0,1]
	v_pk_fma_f32 v[58:59], v[54:55], v[82:83], v[58:59] neg_lo:[0,0,1] neg_hi:[0,0,1]
	v_pk_fma_f32 v[64:65], v[56:57], v[88:89], v[64:65]
	v_pk_fma_f32 v[62:63], v[54:55], v[86:87], v[62:63]
	v_cndmask_b32_e32 v57, v57, v61, vcc
	v_cndmask_b32_e32 v56, v56, v60, vcc
	v_cndmask_b32_e32 v55, v55, v59, vcc
	v_cndmask_b32_e32 v54, v54, v58, vcc
	v_cndmask_b32_e32 v53, v53, v65, vcc
	v_cndmask_b32_e32 v52, v52, v64, vcc
	v_cndmask_b32_e32 v51, v51, v63, vcc
	v_cndmask_b32_e32 v50, v50, v62, vcc
	v_pk_mul_f32 v[58:59], v[56:57], s[28:29] op_sel_hi:[1,0]
	v_pk_mul_f32 v[60:61], v[54:55], s[28:29] op_sel_hi:[1,0]
	v_pk_mul_f32 v[62:63], v[52:53], s[28:29] op_sel_hi:[1,0]
	v_pk_mul_f32 v[64:65], v[50:51], s[28:29] op_sel_hi:[1,0]
	v_cndmask_b32_e64 v56, v56, v58, s[44:45]
	v_cndmask_b32_e64 v57, v57, v59, s[44:45]
	v_cndmask_b32_e64 v54, v54, v60, s[44:45]
	v_cndmask_b32_e64 v55, v55, v61, s[44:45]
	v_cndmask_b32_e64 v58, v52, v62, s[44:45]
	v_cndmask_b32_e64 v53, v53, v63, s[44:45]
	v_cndmask_b32_e64 v52, v50, v64, s[44:45]
	v_cndmask_b32_e64 v59, v51, v65, s[44:45]
	v_cvt_pk_bf16_f32 v50, v54, v55
	v_cvt_pk_bf16_f32 v51, v56, v57
	v_cvt_pk_bf16_f32 v52, v52, v59
	v_cvt_pk_bf16_f32 v53, v58, v53
	ds_bpermute_b32 v50, v248, v50
	ds_bpermute_b32 v51, v248, v51
	ds_bpermute_b32 v52, v248, v52
	ds_bpermute_b32 v53, v248, v53
	v_lshl_add_u64 v[254:255], v[100:101], 0, v[252:253]
	s_waitcnt lgkmcnt(0)
	global_store_dwordx4 v[254:255], v[50:53], off offset:256
	v_pk_add_f32 v[44:45], v[44:45], v[92:93]
	v_pk_add_f32 v[42:43], v[42:43], v[90:91]
	v_mad_u64_u32 v[50:51], s[0:1], v98, s85, v[102:103]
	v_mov_b32_e32 v52, v51
	v_mad_u64_u32 v[52:53], s[0:1], v99, s85, v[52:53]
	v_pk_add_f32 v[48:49], v[48:49], v[96:97]
	v_pk_add_f32 v[46:47], v[46:47], v[94:95]
	s_waitcnt vmcnt(2)
	v_pk_mul_f32 v[54:55], v[44:45], v[68:69]
	v_pk_mul_f32 v[56:57], v[42:43], v[70:71]
	v_pk_mul_f32 v[58:59], v[44:45], v[72:73]
	v_mov_b32_e32 v51, v52
	v_pk_mul_f32 v[52:53], v[42:43], v[66:67]
	v_pk_fma_f32 v[54:55], v[48:49], v[72:73], v[54:55] neg_lo:[0,0,1] neg_hi:[0,0,1]
	v_pk_fma_f32 v[58:59], v[48:49], v[68:69], v[58:59]
	v_pk_fma_f32 v[56:57], v[46:47], v[66:67], v[56:57]
	v_pk_fma_f32 v[52:53], v[46:47], v[70:71], v[52:53] neg_lo:[0,0,1] neg_hi:[0,0,1]
	v_cndmask_b32_e64 v49, v49, v55, s[40:41]
	v_cndmask_b32_e64 v48, v48, v54, s[40:41]
	v_cndmask_b32_e64 v45, v45, v59, s[40:41]
	v_cndmask_b32_e64 v44, v44, v58, s[40:41]
	v_cndmask_b32_e64 v43, v43, v57, s[40:41]
	v_cndmask_b32_e64 v42, v42, v56, s[40:41]
	v_cndmask_b32_e64 v47, v47, v53, s[40:41]
	v_cndmask_b32_e64 v46, v46, v52, s[40:41]
	v_pk_mul_f32 v[52:53], v[48:49], s[28:29] op_sel_hi:[1,0]
	v_pk_mul_f32 v[56:57], v[44:45], s[28:29] op_sel_hi:[1,0]
	v_pk_mul_f32 v[58:59], v[42:43], s[28:29] op_sel_hi:[1,0]
	v_pk_mul_f32 v[54:55], v[46:47], s[28:29] op_sel_hi:[1,0]
	v_cndmask_b32_e64 v48, v48, v52, s[42:43]
	v_cndmask_b32_e64 v52, v44, v56, s[42:43]
	v_cndmask_b32_e64 v45, v45, v57, s[42:43]
	v_cndmask_b32_e64 v44, v42, v58, s[42:43]
	v_lshl_add_u64 v[50:51], v[50:51], 0, v[186:187]
	v_cndmask_b32_e64 v49, v49, v53, s[42:43]
	v_cndmask_b32_e64 v46, v46, v54, s[42:43]
	v_cndmask_b32_e64 v47, v47, v55, s[42:43]
	v_cndmask_b32_e64 v53, v43, v59, s[42:43]
	v_cvt_pk_bf16_f32 v42, v46, v47
	v_cvt_pk_bf16_f32 v43, v48, v49
	v_cvt_pk_bf16_f32 v44, v44, v53
	v_cvt_pk_bf16_f32 v45, v52, v45
	v_pk_add_f32 v[36:37], v[36:37], v[76:77]
	v_pk_add_f32 v[34:35], v[34:35], v[74:75]
	ds_bpermute_b32 v42, v248, v42
	ds_bpermute_b32 v43, v248, v43
	ds_bpermute_b32 v44, v248, v44
	ds_bpermute_b32 v45, v248, v45
	v_lshl_add_u64 v[254:255], v[50:51], 0, v[252:253]
	s_waitcnt lgkmcnt(0)
	global_store_dwordx4 v[254:255], v[42:45], off
	v_pk_add_f32 v[40:41], v[40:41], v[80:81]
	v_pk_add_f32 v[38:39], v[38:39], v[78:79]
	v_pk_mul_f32 v[44:45], v[36:37], v[68:69]
	v_pk_mul_f32 v[46:47], v[34:35], v[70:71]
	v_pk_mul_f32 v[48:49], v[36:37], v[72:73]
	v_pk_mul_f32 v[42:43], v[34:35], v[66:67]
	v_pk_fma_f32 v[44:45], v[40:41], v[72:73], v[44:45] neg_lo:[0,0,1] neg_hi:[0,0,1]
	v_pk_fma_f32 v[48:49], v[40:41], v[68:69], v[48:49]
	v_pk_fma_f32 v[46:47], v[38:39], v[66:67], v[46:47]
	v_pk_fma_f32 v[42:43], v[38:39], v[70:71], v[42:43] neg_lo:[0,0,1] neg_hi:[0,0,1]
	v_cndmask_b32_e32 v41, v41, v45, vcc
	v_cndmask_b32_e32 v40, v40, v44, vcc
	v_cndmask_b32_e32 v37, v37, v49, vcc
	v_cndmask_b32_e32 v36, v36, v48, vcc
	v_cndmask_b32_e32 v35, v35, v47, vcc
	v_cndmask_b32_e32 v34, v34, v46, vcc
	v_cndmask_b32_e32 v39, v39, v43, vcc
	v_cndmask_b32_e32 v38, v38, v42, vcc
	v_pk_mul_f32 v[42:43], v[40:41], s[28:29] op_sel_hi:[1,0]
	v_pk_mul_f32 v[46:47], v[36:37], s[28:29] op_sel_hi:[1,0]
	v_pk_mul_f32 v[48:49], v[34:35], s[28:29] op_sel_hi:[1,0]
	v_pk_mul_f32 v[44:45], v[38:39], s[28:29] op_sel_hi:[1,0]
	v_cndmask_b32_e64 v40, v40, v42, s[44:45]
	v_cndmask_b32_e64 v42, v36, v46, s[44:45]
	v_cndmask_b32_e64 v37, v37, v47, s[44:45]
	v_cndmask_b32_e64 v36, v34, v48, s[44:45]
	v_cndmask_b32_e64 v41, v41, v43, s[44:45]
	v_cndmask_b32_e64 v38, v38, v44, s[44:45]
	v_cndmask_b32_e64 v39, v39, v45, s[44:45]
	v_cndmask_b32_e64 v43, v35, v49, s[44:45]
	v_cvt_pk_bf16_f32 v34, v38, v39
	v_cvt_pk_bf16_f32 v35, v40, v41
	v_cvt_pk_bf16_f32 v36, v36, v43
	v_cvt_pk_bf16_f32 v37, v42, v37
	ds_bpermute_b32 v34, v248, v34
	ds_bpermute_b32 v35, v248, v35
	ds_bpermute_b32 v36, v248, v36
	ds_bpermute_b32 v37, v248, v37
	v_lshl_add_u64 v[254:255], v[50:51], 0, v[252:253]
	s_waitcnt lgkmcnt(0)
	global_store_dwordx4 v[254:255], v[34:37], off offset:256
	v_add_u32_e32 v50, 0xb0, v188
	s_and_saveexec_b64 s[0:1], s[58:59]
	s_xor_b64 s[0:1], exec, s[0:1]
	v_ashrrev_i32_e32 v51, 31, v50
	s_or_saveexec_b64 s[0:1], s[0:1]
	v_add_u32_e32 v52, 0xa0, v188
	v_ashrrev_i32_e32 v53, 31, v52
	v_mov_b32_e32 v42, 1.0
	v_mov_b32_e32 v34, 0
	v_mov_b32_e32 v35, 0
	v_mov_b32_e32 v36, 0
	v_mov_b32_e32 v37, 0
	v_mov_b32_e32 v43, 1.0
	v_mov_b32_e32 v44, 1.0
	v_mov_b32_e32 v45, 1.0
	v_mov_b32_e32 v46, 0
	v_mov_b32_e32 v47, 0
	v_mov_b32_e32 v48, 0
	v_mov_b32_e32 v49, 0
	v_mov_b32_e32 v38, 1.0
	v_mov_b32_e32 v39, 1.0
	v_mov_b32_e32 v40, 1.0
	v_mov_b32_e32 v41, 1.0
	s_xor_b64 exec, exec, s[0:1]
	s_cbranch_execz .LBB0_205
	v_lshlrev_b64 v[34:35], 6, v[52:53]
	v_lshl_add_u64 v[34:35], v[180:181], 0, v[34:35]
	v_ashrrev_i32_e32 v51, 31, v50
	global_load_dwordx4 v[42:45], v[34:35], off
	global_load_dwordx4 v[46:49], v[34:35], off offset:32
	v_lshlrev_b64 v[34:35], 6, v[50:51]
	v_lshl_add_u64 v[34:35], v[180:181], 0, v[34:35]
	global_load_dwordx4 v[38:41], v[34:35], off
	s_nop 0
	global_load_dwordx4 v[34:37], v[34:35], off offset:32
; __device__ __forceinline__ unsigned cvt_pk_bf16(float lo, float hi) { unsigned r; asm volatile("v_cvt_pk_bf16_f32 %0, %1, %2" : "=v"(r) : "v"(lo), "v"(hi)); return r; }
;     __device__ __forceinline__ void operator()(const f32x4 (&acc)[2][2][4][2], const Unit& u, int wr, int wc, int fr, int fq) const {
;     ...
;                     f32x4 v0 = acc[ai][bj][m][0] + bv[bj][0], v1 = acc[ai][bj][m][1] + bv[bj][1];
;                     const int cb = colt + bj * HALF;
;                     if (rot_wave && cb < 640) {
;                         const f32x4 t1 = v0, t2 = v1;
;                         v0 = t1 * cc[mm][0] - t2 * cc[mm][1]; v1 = t2 * cc[mm][0] + t1 * cc[mm][1];
;                     }
;                     if (cb < 512) { v0 = v0 * 0.125f; v1 = v1 * 0.125f; }
;                     u32x4 w; w.x = cvt_pk_bf16(v0[0], v0[1]); w.y = cvt_pk_bf16(v0[2], v0[3]); w.z = cvt_pk_bf16(v1[0], v1[1]); w.w = cvt_pk_bf16(v1[2], v1[3]);
;                     *(u32x4*)(rowp + bj * HALF) = w;
.LBB0_205:
	s_or_b64 exec, exec, s[0:1]
	v_pk_add_f32 v[28:29], v[28:29], v[92:93]
	v_pk_add_f32 v[26:27], v[26:27], v[90:91]
	v_pk_add_f32 v[32:33], v[32:33], v[96:97]
	v_pk_add_f32 v[30:31], v[30:31], v[94:95]
	s_waitcnt vmcnt(2)
	v_pk_mul_f32 v[58:59], v[28:29], v[48:49]
	v_pk_mul_f32 v[60:61], v[26:27], v[42:43]
	v_pk_mul_f32 v[62:63], v[28:29], v[44:45]
	v_pk_mul_f32 v[56:57], v[26:27], v[46:47]
	v_pk_fma_f32 v[58:59], v[32:33], v[44:45], v[58:59] neg_lo:[0,0,1] neg_hi:[0,0,1]
	v_pk_fma_f32 v[62:63], v[32:33], v[48:49], v[62:63]
	v_pk_fma_f32 v[60:61], v[30:31], v[46:47], v[60:61]
	v_pk_fma_f32 v[56:57], v[30:31], v[42:43], v[56:57] neg_lo:[0,0,1] neg_hi:[0,0,1]
	v_cndmask_b32_e64 v33, v33, v59, s[40:41]
	v_cndmask_b32_e64 v32, v32, v58, s[40:41]
	v_cndmask_b32_e64 v29, v29, v63, s[40:41]
	v_cndmask_b32_e64 v28, v28, v62, s[40:41]
	v_cndmask_b32_e64 v27, v27, v61, s[40:41]
	v_cndmask_b32_e64 v26, v26, v60, s[40:41]
	v_mov_b64_e32 v[54:55], s[74:75]
	v_cndmask_b32_e64 v31, v31, v57, s[40:41]
	v_cndmask_b32_e64 v30, v30, v56, s[40:41]
	v_pk_mul_f32 v[56:57], v[32:33], s[28:29] op_sel_hi:[1,0]
	v_pk_mul_f32 v[60:61], v[28:29], s[28:29] op_sel_hi:[1,0]
	v_pk_mul_f32 v[62:63], v[26:27], s[28:29] op_sel_hi:[1,0]
	v_mad_i64_i32 v[52:53], s[0:1], v52, s85, v[54:55]
	v_pk_mul_f32 v[58:59], v[30:31], s[28:29] op_sel_hi:[1,0]
	v_cndmask_b32_e64 v32, v32, v56, s[42:43]
	v_cndmask_b32_e64 v56, v28, v60, s[42:43]
	v_cndmask_b32_e64 v29, v29, v61, s[42:43]
	v_cndmask_b32_e64 v28, v26, v62, s[42:43]
	v_lshl_add_u64 v[52:53], v[52:53], 0, v[186:187]
	v_cndmask_b32_e64 v33, v33, v57, s[42:43]
	v_cndmask_b32_e64 v30, v30, v58, s[42:43]
	v_cndmask_b32_e64 v31, v31, v59, s[42:43]
	v_cndmask_b32_e64 v57, v27, v63, s[42:43]
	v_cvt_pk_bf16_f32 v26, v30, v31
	v_cvt_pk_bf16_f32 v27, v32, v33
	v_cvt_pk_bf16_f32 v28, v28, v57
	v_cvt_pk_bf16_f32 v29, v56, v29
	v_pk_add_f32 v[20:21], v[20:21], v[76:77]
	v_pk_add_f32 v[18:19], v[18:19], v[74:75]
	ds_bpermute_b32 v26, v248, v26
	ds_bpermute_b32 v27, v248, v27
	ds_bpermute_b32 v28, v248, v28
	ds_bpermute_b32 v29, v248, v29
	v_lshl_add_u64 v[254:255], v[52:53], 0, v[252:253]
	s_waitcnt lgkmcnt(0)
	global_store_dwordx4 v[254:255], v[26:29], off
	v_pk_add_f32 v[24:25], v[24:25], v[80:81]
	v_pk_add_f32 v[22:23], v[22:23], v[78:79]
	v_pk_mul_f32 v[26:27], v[18:19], v[46:47]
	v_pk_mul_f32 v[28:29], v[20:21], v[48:49]
	v_pk_mul_f32 v[30:31], v[18:19], v[42:43]
	v_pk_mul_f32 v[32:33], v[20:21], v[44:45]
	v_pk_fma_f32 v[28:29], v[24:25], v[44:45], v[28:29] neg_lo:[0,0,1] neg_hi:[0,0,1]
	v_pk_fma_f32 v[26:27], v[22:23], v[42:43], v[26:27] neg_lo:[0,0,1] neg_hi:[0,0,1]
	v_pk_fma_f32 v[32:33], v[24:25], v[48:49], v[32:33]
	v_pk_fma_f32 v[30:31], v[22:23], v[46:47], v[30:31]
	v_cndmask_b32_e32 v25, v25, v29, vcc
	v_cndmask_b32_e32 v24, v24, v28, vcc
	v_cndmask_b32_e32 v23, v23, v27, vcc
	v_cndmask_b32_e32 v22, v22, v26, vcc
	v_cndmask_b32_e32 v21, v21, v33, vcc
	v_cndmask_b32_e32 v20, v20, v32, vcc
	v_cndmask_b32_e32 v19, v19, v31, vcc
	v_cndmask_b32_e32 v18, v18, v30, vcc
	v_pk_mul_f32 v[26:27], v[24:25], s[28:29] op_sel_hi:[1,0]
	v_pk_mul_f32 v[28:29], v[22:23], s[28:29] op_sel_hi:[1,0]
	v_pk_mul_f32 v[30:31], v[20:21], s[28:29] op_sel_hi:[1,0]
	v_pk_mul_f32 v[32:33], v[18:19], s[28:29] op_sel_hi:[1,0]
	v_cndmask_b32_e64 v24, v24, v26, s[44:45]
	v_cndmask_b32_e64 v25, v25, v27, s[44:45]
	v_cndmask_b32_e64 v22, v22, v28, s[44:45]
	v_cndmask_b32_e64 v23, v23, v29, s[44:45]
	v_cndmask_b32_e64 v26, v20, v30, s[44:45]
	v_cndmask_b32_e64 v21, v21, v31, s[44:45]
	v_cndmask_b32_e64 v20, v18, v32, s[44:45]
	v_cndmask_b32_e64 v27, v19, v33, s[44:45]
	v_cvt_pk_bf16_f32 v18, v22, v23
	v_cvt_pk_bf16_f32 v19, v24, v25
	v_cvt_pk_bf16_f32 v20, v20, v27
	v_cvt_pk_bf16_f32 v21, v26, v21
	ds_bpermute_b32 v18, v248, v18
	ds_bpermute_b32 v19, v248, v19
	ds_bpermute_b32 v20, v248, v20
	ds_bpermute_b32 v21, v248, v21
	v_lshl_add_u64 v[254:255], v[52:53], 0, v[252:253]
	s_waitcnt lgkmcnt(0)
; __device__ __forceinline__ unsigned cvt_pk_bf16(float lo, float hi) { unsigned r; asm volatile("v_cvt_pk_bf16_f32 %0, %1, %2" : "=v"(r) : "v"(lo), "v"(hi)); return r; }
; #define PG8_BAR __builtin_amdgcn_s_barrier()
;     ...
;         if constexpr (!Epi::AFTER_DRAIN) { E(acc, cur, wr, wc, fr, fq); S.done(cur); }
;         if (!has_next) break;
; #pragma unroll
;         for (int a = 0; a < 2; ++a)
; #pragma unroll
;             for (int b = 0; b < 2; ++b)
; #pragma unroll
;                 for (int m = 0; m < 4; ++m)
; #pragma unroll
;                     for (int n = 0; n < 2; ++n) acc[a][b][m][n] = (f32x4){0.f, 0.f, 0.f, 0.f};
;         cur = nxt; cA = nA; cB = nB; ++ui;
;         if constexpr (ALIGN_EPI) { if (wr == 1) PG8_BAR; }
;     }
;     __device__ __forceinline__ void operator()(const f32x4 (&acc)[2][2][4][2], const Unit& u, int wr, int wc, int fr, int fq) const {
;     ...
;                     f32x4 v0 = acc[ai][bj][m][0] + bv[bj][0], v1 = acc[ai][bj][m][1] + bv[bj][1];
;                     const int cb = colt + bj * HALF;
;                     if (rot_wave && cb < 640) {
;                         const f32x4 t1 = v0, t2 = v1;
;                         v0 = t1 * cc[mm][0] - t2 * cc[mm][1]; v1 = t2 * cc[mm][0] + t1 * cc[mm][1];
;                     }
;                     if (cb < 512) { v0 = v0 * 0.125f; v1 = v1 * 0.125f; }
;                     u32x4 w; w.x = cvt_pk_bf16(v0[0], v0[1]); w.y = cvt_pk_bf16(v0[2], v0[3]); w.z = cvt_pk_bf16(v1[0], v1[1]); w.w = cvt_pk_bf16(v1[2], v1[3]);
;                     *(u32x4*)(rowp + bj * HALF) = w;
	global_store_dwordx4 v[254:255], v[18:21], off offset:256
	v_pk_add_f32 v[12:13], v[12:13], v[92:93]
	v_pk_add_f32 v[10:11], v[10:11], v[90:91]
	v_mad_u64_u32 v[18:19], s[0:1], v50, s85, v[54:55]
	v_mov_b32_e32 v20, v19
	v_mad_u64_u32 v[20:21], s[0:1], v51, s85, v[20:21]
	v_pk_add_f32 v[16:17], v[16:17], v[96:97]
	v_pk_add_f32 v[14:15], v[14:15], v[94:95]
	s_waitcnt vmcnt(2)
	v_pk_mul_f32 v[22:23], v[12:13], v[36:37]
	v_pk_mul_f32 v[24:25], v[10:11], v[38:39]
	v_pk_mul_f32 v[26:27], v[12:13], v[40:41]
	v_mov_b32_e32 v19, v20
	v_pk_mul_f32 v[20:21], v[10:11], v[34:35]
	v_pk_fma_f32 v[22:23], v[16:17], v[40:41], v[22:23] neg_lo:[0,0,1] neg_hi:[0,0,1]
	v_pk_fma_f32 v[26:27], v[16:17], v[36:37], v[26:27]
	v_pk_fma_f32 v[24:25], v[14:15], v[34:35], v[24:25]
	v_pk_fma_f32 v[20:21], v[14:15], v[38:39], v[20:21] neg_lo:[0,0,1] neg_hi:[0,0,1]
	v_cndmask_b32_e64 v17, v17, v23, s[40:41]
	v_cndmask_b32_e64 v16, v16, v22, s[40:41]
	v_cndmask_b32_e64 v13, v13, v27, s[40:41]
	v_cndmask_b32_e64 v12, v12, v26, s[40:41]
	v_cndmask_b32_e64 v11, v11, v25, s[40:41]
	v_cndmask_b32_e64 v10, v10, v24, s[40:41]
	v_cndmask_b32_e64 v15, v15, v21, s[40:41]
	v_cndmask_b32_e64 v14, v14, v20, s[40:41]
	v_pk_mul_f32 v[20:21], v[16:17], s[28:29] op_sel_hi:[1,0]
	v_pk_mul_f32 v[24:25], v[12:13], s[28:29] op_sel_hi:[1,0]
	v_pk_mul_f32 v[26:27], v[10:11], s[28:29] op_sel_hi:[1,0]
	v_pk_mul_f32 v[22:23], v[14:15], s[28:29] op_sel_hi:[1,0]
	v_cndmask_b32_e64 v16, v16, v20, s[42:43]
	v_cndmask_b32_e64 v20, v12, v24, s[42:43]
	v_cndmask_b32_e64 v13, v13, v25, s[42:43]
	v_cndmask_b32_e64 v12, v10, v26, s[42:43]
	v_lshl_add_u64 v[18:19], v[18:19], 0, v[186:187]
	v_cndmask_b32_e64 v17, v17, v21, s[42:43]
	v_cndmask_b32_e64 v14, v14, v22, s[42:43]
	v_cndmask_b32_e64 v15, v15, v23, s[42:43]
	v_cndmask_b32_e64 v21, v11, v27, s[42:43]
	v_cvt_pk_bf16_f32 v10, v14, v15
	v_cvt_pk_bf16_f32 v11, v16, v17
	v_cvt_pk_bf16_f32 v12, v12, v21
	v_cvt_pk_bf16_f32 v13, v20, v13
	v_pk_add_f32 v[4:5], v[4:5], v[76:77]
	v_pk_add_f32 v[2:3], v[2:3], v[74:75]
	ds_bpermute_b32 v10, v248, v10
	ds_bpermute_b32 v11, v248, v11
	ds_bpermute_b32 v12, v248, v12
	ds_bpermute_b32 v13, v248, v13
	v_lshl_add_u64 v[254:255], v[18:19], 0, v[252:253]
	s_waitcnt lgkmcnt(0)
	global_store_dwordx4 v[254:255], v[10:13], off
	v_pk_add_f32 v[8:9], v[8:9], v[80:81]
	v_pk_add_f32 v[6:7], v[6:7], v[78:79]
	v_pk_mul_f32 v[12:13], v[4:5], v[36:37]
	v_pk_mul_f32 v[14:15], v[2:3], v[38:39]
	v_pk_mul_f32 v[16:17], v[4:5], v[40:41]
	v_pk_mul_f32 v[10:11], v[2:3], v[34:35]
	v_pk_fma_f32 v[12:13], v[8:9], v[40:41], v[12:13] neg_lo:[0,0,1] neg_hi:[0,0,1]
	v_pk_fma_f32 v[16:17], v[8:9], v[36:37], v[16:17]
	v_pk_fma_f32 v[14:15], v[6:7], v[34:35], v[14:15]
	v_pk_fma_f32 v[10:11], v[6:7], v[38:39], v[10:11] neg_lo:[0,0,1] neg_hi:[0,0,1]
	v_cndmask_b32_e32 v9, v9, v13, vcc
	v_cndmask_b32_e32 v8, v8, v12, vcc
	v_cndmask_b32_e32 v5, v5, v17, vcc
	v_cndmask_b32_e32 v4, v4, v16, vcc
	v_cndmask_b32_e32 v3, v3, v15, vcc
	v_cndmask_b32_e32 v2, v2, v14, vcc
	v_cndmask_b32_e32 v7, v7, v11, vcc
	v_cndmask_b32_e32 v6, v6, v10, vcc
	v_pk_mul_f32 v[10:11], v[8:9], s[28:29] op_sel_hi:[1,0]
	v_pk_mul_f32 v[14:15], v[4:5], s[28:29] op_sel_hi:[1,0]
	v_pk_mul_f32 v[16:17], v[2:3], s[28:29] op_sel_hi:[1,0]
	v_pk_mul_f32 v[12:13], v[6:7], s[28:29] op_sel_hi:[1,0]
	v_cndmask_b32_e64 v8, v8, v10, s[44:45]
	v_cndmask_b32_e64 v10, v4, v14, s[44:45]
	v_cndmask_b32_e64 v5, v5, v15, s[44:45]
	v_cndmask_b32_e64 v4, v2, v16, s[44:45]
	s_andn2_b64 vcc, exec, s[38:39]
	s_mov_b64 s[0:1], -1
	v_cndmask_b32_e64 v9, v9, v11, s[44:45]
	v_cndmask_b32_e64 v6, v6, v12, s[44:45]
	v_cndmask_b32_e64 v7, v7, v13, s[44:45]
	v_cndmask_b32_e64 v11, v3, v17, s[44:45]
	v_cvt_pk_bf16_f32 v2, v6, v7
	v_cvt_pk_bf16_f32 v3, v8, v9
	v_cvt_pk_bf16_f32 v4, v4, v11
	v_cvt_pk_bf16_f32 v5, v10, v5
	ds_bpermute_b32 v2, v248, v2
	ds_bpermute_b32 v3, v248, v3
	ds_bpermute_b32 v4, v248, v4
	ds_bpermute_b32 v5, v248, v5
	v_lshl_add_u64 v[254:255], v[18:19], 0, v[252:253]
	s_waitcnt lgkmcnt(0)
	global_store_dwordx4 v[254:255], v[2:5], off offset:256
	s_cbranch_vccnz .LBB0_182
	s_andn2_b64 vcc, exec, s[20:21]
	s_cbranch_vccnz .LBB0_181
	s_barrier
	s_branch .LBB0_181

; __global__ void __launch_bounds__(512, 2) fwd_kernel(Args a) {
	.amdhsa_kernel _Z10fwd_kernel4Args
		.amdhsa_group_segment_fixed_size 0
		.amdhsa_private_segment_fixed_size 0
		.amdhsa_kernarg_size 416
		.amdhsa_user_sgpr_count 2
		.amdhsa_user_sgpr_dispatch_ptr 0
		.amdhsa_user_sgpr_queue_ptr 0
		.amdhsa_user_sgpr_kernarg_segment_ptr 1
		.amdhsa_user_sgpr_dispatch_id 0
		.amdhsa_user_sgpr_kernarg_preload_length 0
		.amdhsa_user_sgpr_kernarg_preload_offset 0
		.amdhsa_user_sgpr_private_segment_size 0
		.amdhsa_uses_dynamic_stack 0
		.amdhsa_enable_private_segment 0
		.amdhsa_system_sgpr_workgroup_id_x 1
		.amdhsa_system_sgpr_workgroup_id_y 0
		.amdhsa_system_sgpr_workgroup_id_z 0
		.amdhsa_system_sgpr_workgroup_info 0
		.amdhsa_system_vgpr_workitem_id 2
		.amdhsa_next_free_vgpr 256
		.amdhsa_next_free_sgpr 102
		.amdhsa_accum_offset 256
		.amdhsa_reserve_vcc 1
		.amdhsa_float_round_mode_32 0
		.amdhsa_float_round_mode_16_64 0
		.amdhsa_float_denorm_mode_32 3
		.amdhsa_float_denorm_mode_16_64 3
		.amdhsa_dx10_clamp 1
		.amdhsa_ieee_mode 1
		.amdhsa_fp16_overflow 0
		.amdhsa_tg_split 0
		.amdhsa_exception_fp_ieee_invalid_op 0
		.amdhsa_exception_fp_denorm_src 0
		.amdhsa_exception_fp_ieee_div_zero 0
		.amdhsa_exception_fp_ieee_overflow 0
		.amdhsa_exception_fp_ieee_underflow 0
		.amdhsa_exception_fp_ieee_inexact 0
		.amdhsa_exception_int_div_zero 0
	.end_amdhsa_kernel

; __global__ void __launch_bounds__(512, 2) fwd_kernel(Args a) {
amdhsa.kernels:
  - .agpr_count:     0
    .args:
      - .offset:         0
        .size:           160
        .value_kind:     by_value
      - .offset:         160
        .size:           4
        .value_kind:     hidden_block_count_x
      - .offset:         164
        .size:           4
        .value_kind:     hidden_block_count_y
      - .offset:         168
        .size:           4
        .value_kind:     hidden_block_count_z
      - .offset:         172
        .size:           2
        .value_kind:     hidden_group_size_x
      - .offset:         174
        .size:           2
        .value_kind:     hidden_group_size_y
      - .offset:         176
        .size:           2
        .value_kind:     hidden_group_size_z
      - .offset:         178
        .size:           2
        .value_kind:     hidden_remainder_x
      - .offset:         180
        .size:           2
        .value_kind:     hidden_remainder_y
      - .offset:         182
        .size:           2
        .value_kind:     hidden_remainder_z
      - .offset:         200
        .size:           8
        .value_kind:     hidden_global_offset_x
      - .offset:         208
        .size:           8
        .value_kind:     hidden_global_offset_y
      - .offset:         216
        .size:           8
        .value_kind:     hidden_global_offset_z
      - .offset:         224
        .size:           2
        .value_kind:     hidden_grid_dims
      - .offset:         248
        .size:           8
        .value_kind:     hidden_multigrid_sync_arg
      - .offset:         280
        .size:           4
        .value_kind:     hidden_dynamic_lds_size
    .group_segment_fixed_size: 0
    .kernarg_segment_align: 8
    .kernarg_segment_size: 416
    .language:       OpenCL C
    .language_version:
      - 2
      - 0
    .max_flat_workgroup_size: 512
    .name:           _Z10fwd_kernel4Args
    .private_segment_fixed_size: 0
    .sgpr_count:     108
    .sgpr_spill_count: 158
    .symbol:         _Z10fwd_kernel4Args.kd
    .uniform_work_group_size: 1
    .uses_dynamic_stack: false
    .vgpr_count:     256
    .vgpr_spill_count: 0
    .wavefront_size: 64
